# exec-only-global-barriers-6-7,8-9,14-15+EpiRes-permlane-row-sums
# speedup vs baseline: 1.0030x; 1.0030x over previous
.LBB0_316:
	v_lshl_or_b32 v158, s68, 8, v221
	v_lshl_add_u32 v160, s87, 8, v220
	v_ashrrev_i32_e32 v159, 31, v158
	s_waitcnt lgkmcnt(0)
	v_lshlrev_b64 v[182:183], 1, v[158:159]
	v_ashrrev_i32_e32 v161, 31, v160
	v_lshl_add_u64 v[162:163], s[22:23], 0, v[182:183]
	v_lshlrev_b64 v[184:185], 11, v[160:161]
	v_lshl_add_u64 v[130:131], v[162:163], 0, v[184:185]
	global_load_dwordx4 v[178:181], v[130:131], off
	global_load_dwordx4 v[154:157], v[130:131], off offset:256
	v_or_b32_e32 v172, 16, v160
	v_ashrrev_i32_e32 v173, 31, v172
	v_or_b32_e32 v168, 32, v160
	v_lshlrev_b64 v[174:175], 11, v[172:173]
	v_ashrrev_i32_e32 v169, 31, v168
	v_or_b32_e32 v164, 48, v160
	v_lshl_add_u64 v[130:131], v[162:163], 0, v[174:175]
	v_lshlrev_b64 v[170:171], 11, v[168:169]
	v_ashrrev_i32_e32 v165, 31, v164
	global_load_dwordx4 v[150:153], v[130:131], off
	global_load_dwordx4 v[146:149], v[130:131], off offset:256
	v_lshl_add_u64 v[130:131], v[162:163], 0, v[170:171]
	v_lshlrev_b64 v[166:167], 11, v[164:165]
	global_load_dwordx4 v[142:145], v[130:131], off
	global_load_dwordx4 v[138:141], v[130:131], off offset:256
	v_lshl_add_u64 v[130:131], v[162:163], 0, v[166:167]
	global_load_dwordx4 v[134:137], v[130:131], off
	s_nop 0
	global_load_dwordx4 v[130:133], v[130:131], off offset:256
	v_lshl_add_u64 v[184:185], s[22:23], 0, v[184:185]
	v_lshl_add_u64 v[182:183], v[184:185], 0, v[182:183]
	v_cmp_lt_i32_e32 vcc, v233, v228
	s_lshl_b32 s30, s68, 2
	s_ashr_i32 s31, s30, 31
	v_cndmask_b32_e32 v96, v227, v233, vcc
	v_lshlrev_b32_e32 v176, 2, v96
	v_cmp_lt_i32_e32 vcc, v234, v228
	s_waitcnt vmcnt(0)
	v_lshlrev_b32_e32 v186, 16, v178
	v_and_b32_e32 v187, 0xffff0000, v178
	v_lshlrev_b32_e32 v178, 16, v179
	v_and_b32_e32 v179, 0xffff0000, v179
	v_lshlrev_b32_e32 v188, 16, v180
	v_and_b32_e32 v189, 0xffff0000, v180
	v_lshlrev_b32_e32 v180, 16, v181
	v_and_b32_e32 v181, 0xffff0000, v181
	v_pk_add_f32 v[128:129], v[128:129], v[178:179]
	v_pk_add_f32 v[126:127], v[126:127], v[186:187]
	v_pk_add_f32 v[178:179], v[124:125], v[180:181]
	v_pk_add_f32 v[180:181], v[122:123], v[188:189]
	v_cvt_pk_bf16_f32 v122, v126, v127
	v_cvt_pk_bf16_f32 v123, v128, v129
	v_cvt_pk_bf16_f32 v124, v180, v181
	v_cvt_pk_bf16_f32 v125, v178, v179
	global_store_dwordx4 v[182:183], v[122:125], off
	v_cndmask_b32_e32 v96, v227, v234, vcc
	v_lshlrev_b32_e32 v96, 2, v96
	v_mul_f32_e32 v122, v127, v127
	v_mul_f32_e32 v123, v129, v129
	v_fmac_f32_e32 v122, v126, v126
	v_fmac_f32_e32 v123, v128, v128
	v_add_f32_e32 v122, v122, v123
	v_mul_f32_e32 v123, v181, v181
	v_fmac_f32_e32 v123, v180, v180
	v_add_f32_e32 v122, v123, v122
	v_mul_f32_e32 v123, v179, v179
	v_fmac_f32_e32 v123, v178, v178
	v_add_f32_e32 v177, v123, v122
	v_lshlrev_b32_e32 v122, 16, v154
	v_and_b32_e32 v123, 0xffff0000, v154
	v_lshlrev_b32_e32 v124, 16, v155
	v_and_b32_e32 v125, 0xffff0000, v155
	v_lshlrev_b32_e32 v126, 16, v156
	v_and_b32_e32 v127, 0xffff0000, v156
	v_lshlrev_b32_e32 v128, 16, v157
	v_and_b32_e32 v129, 0xffff0000, v157
	v_pk_add_f32 v[120:121], v[120:121], v[124:125]
	v_pk_add_f32 v[118:119], v[118:119], v[122:123]
	v_pk_add_f32 v[122:123], v[116:117], v[128:129]
	v_pk_add_f32 v[124:125], v[114:115], v[126:127]
	v_cvt_pk_bf16_f32 v114, v118, v119
	v_cvt_pk_bf16_f32 v115, v120, v121
	v_cvt_pk_bf16_f32 v116, v124, v125
	v_cvt_pk_bf16_f32 v117, v122, v123
	global_store_dwordx4 v[182:183], v[114:117], off offset:256
	s_nop 1
	v_mul_f32_e32 v114, v119, v119
	v_mul_f32_e32 v115, v121, v121
	v_fmac_f32_e32 v114, v118, v118
	v_fmac_f32_e32 v115, v120, v120
	v_add_f32_e32 v114, v114, v115
	v_mul_f32_e32 v115, v125, v125
	v_fmac_f32_e32 v115, v124, v124
	v_add_f32_e32 v114, v115, v114
	v_mul_f32_e32 v115, v123, v123
	v_fmac_f32_e32 v115, v122, v122
	v_add_f32_e32 v114, v115, v114
	v_add_f32_e32 v114, v177, v114
	v_mov_b32_e32 v115, v114
	s_nop 1
	v_permlane16_swap_b32_e32 v114, v115
	v_add_f32_e32 v114, v114, v115
	v_mov_b32_e32 v115, v114
	s_nop 1
	v_permlane32_swap_b32_e32 v114, v115
	v_add_f32_e32 v114, v114, v115
	s_and_saveexec_b64 s[40:41], s[36:37]
	s_cbranch_execz .LBB0_318
	v_readlane_b32 s42, v252, 26
	v_lshlrev_b64 v[116:117], 6, v[160:161]
	v_readlane_b32 s43, v252, 27
	s_lshl_b32 s68, s13, 2
	v_lshl_add_u64 v[116:117], s[42:43], 0, v[116:117]
	v_lshl_add_u64 v[116:117], s[30:31], 2, v[116:117]
	v_lshl_add_u64 v[116:117], v[116:117], 0, s[68:69]
	global_store_dword v[116:117], v114, off
.LBB0_318:
	s_or_b64 exec, exec, s[40:41]
	v_lshlrev_b32_e32 v114, 16, v150
	s_waitcnt lgkmcnt(0)
	v_and_b32_e32 v115, 0xffff0000, v150
	v_lshlrev_b32_e32 v116, 16, v151
	v_and_b32_e32 v117, 0xffff0000, v151
	v_lshlrev_b32_e32 v118, 16, v152
	v_and_b32_e32 v119, 0xffff0000, v152
	v_pk_add_f32 v[110:111], v[110:111], v[114:115]
	v_pk_add_f32 v[112:113], v[112:113], v[116:117]
	v_pk_add_f32 v[116:117], v[106:107], v[118:119]
	v_cvt_pk_bf16_f32 v106, v110, v111
	v_mul_f32_e32 v111, v111, v111
	v_fmac_f32_e32 v111, v110, v110
	v_mul_f32_e32 v110, v113, v113
	v_fmac_f32_e32 v110, v112, v112
	v_lshlrev_b32_e32 v120, 16, v153
	v_and_b32_e32 v121, 0xffff0000, v153
	v_add_f32_e32 v110, v111, v110
	v_mul_f32_e32 v111, v117, v117
	v_pk_add_f32 v[114:115], v[108:109], v[120:121]
	v_fmac_f32_e32 v111, v116, v116
	v_add_f32_e32 v110, v111, v110
	v_mul_f32_e32 v111, v115, v115
	v_fmac_f32_e32 v111, v114, v114
	v_cvt_pk_bf16_f32 v107, v112, v113
	v_add_f32_e32 v118, v111, v110
	v_lshlrev_b32_e32 v110, 16, v146
	v_and_b32_e32 v111, 0xffff0000, v146
	v_lshlrev_b32_e32 v112, 16, v147
	v_and_b32_e32 v113, 0xffff0000, v147
	v_cvt_pk_bf16_f32 v109, v114, v115
	v_lshlrev_b32_e32 v114, 16, v148
	v_and_b32_e32 v115, 0xffff0000, v148
	v_pk_add_f32 v[104:105], v[104:105], v[112:113]
	v_pk_add_f32 v[102:103], v[102:103], v[110:111]
	v_pk_add_f32 v[112:113], v[98:99], v[114:115]
	v_mul_f32_e32 v98, v103, v103
	v_mul_f32_e32 v99, v105, v105
	v_fmac_f32_e32 v98, v102, v102
	v_fmac_f32_e32 v99, v104, v104
	v_cvt_pk_bf16_f32 v108, v116, v117
	v_lshlrev_b32_e32 v116, 16, v149
	v_and_b32_e32 v117, 0xffff0000, v149
	v_add_f32_e32 v98, v98, v99
	v_mul_f32_e32 v99, v113, v113
	v_pk_add_f32 v[110:111], v[100:101], v[116:117]
	v_fmac_f32_e32 v99, v112, v112
	v_add_f32_e32 v98, v99, v98
	v_mul_f32_e32 v99, v111, v111
	v_fmac_f32_e32 v99, v110, v110
	v_add_f32_e32 v98, v99, v98
	v_add_f32_e32 v101, v118, v98
	v_mov_b32_e32 v116, v101
	s_nop 1
	v_permlane16_swap_b32_e32 v101, v116
	v_lshl_add_u64 v[98:99], s[22:23], 0, v[174:175]
	v_lshl_add_u64 v[114:115], v[158:159], 1, v[98:99]
	v_cvt_pk_bf16_f32 v100, v102, v103
	v_cvt_pk_bf16_f32 v102, v112, v113
	v_add_f32_e32 v98, v101, v116
	v_mov_b32_e32 v99, v98
	s_nop 1
	v_permlane32_swap_b32_e32 v98, v99
	v_add_f32_e32 v98, v98, v99
	v_cvt_pk_bf16_f32 v101, v104, v105
	v_cvt_pk_bf16_f32 v103, v110, v111
	global_store_dwordx4 v[114:115], v[106:109], off
	global_store_dwordx4 v[114:115], v[100:103], off offset:256
	s_and_saveexec_b64 s[40:41], s[36:37]
	s_cbranch_execz .LBB0_320
	v_readlane_b32 s42, v252, 26
	v_lshlrev_b64 v[100:101], 6, v[172:173]
	v_readlane_b32 s43, v252, 27
	s_lshl_b32 s68, s13, 2
	v_lshl_add_u64 v[100:101], s[42:43], 0, v[100:101]
	v_lshl_add_u64 v[100:101], s[30:31], 2, v[100:101]
	v_lshl_add_u64 v[100:101], v[100:101], 0, s[68:69]
	global_store_dword v[100:101], v98, off
.LBB0_320:
	s_or_b64 exec, exec, s[40:41]
	v_lshlrev_b32_e32 v98, 16, v142
	s_waitcnt lgkmcnt(0)
	v_and_b32_e32 v99, 0xffff0000, v142
	v_lshlrev_b32_e32 v100, 16, v143
	v_and_b32_e32 v101, 0xffff0000, v143
	v_lshlrev_b32_e32 v102, 16, v144
	v_and_b32_e32 v103, 0xffff0000, v144
	v_pk_add_f32 v[92:93], v[92:93], v[98:99]
	v_pk_add_f32 v[94:95], v[94:95], v[100:101]
	v_pk_add_f32 v[100:101], v[88:89], v[102:103]
	v_cvt_pk_bf16_f32 v88, v92, v93
	v_mul_f32_e32 v93, v93, v93
	v_fmac_f32_e32 v93, v92, v92
	v_mul_f32_e32 v92, v95, v95
	v_fmac_f32_e32 v92, v94, v94
	v_lshlrev_b32_e32 v104, 16, v145
	v_and_b32_e32 v105, 0xffff0000, v145
	v_add_f32_e32 v92, v93, v92
	v_mul_f32_e32 v93, v101, v101
	v_pk_add_f32 v[98:99], v[90:91], v[104:105]
	v_fmac_f32_e32 v93, v100, v100
	v_add_f32_e32 v92, v93, v92
	v_mul_f32_e32 v93, v99, v99
	v_fmac_f32_e32 v93, v98, v98
	v_cvt_pk_bf16_f32 v89, v94, v95
	v_add_f32_e32 v102, v93, v92
	v_lshlrev_b32_e32 v92, 16, v138
	v_and_b32_e32 v93, 0xffff0000, v138
	v_lshlrev_b32_e32 v94, 16, v139
	v_and_b32_e32 v95, 0xffff0000, v139
	v_cvt_pk_bf16_f32 v91, v98, v99
	v_lshlrev_b32_e32 v98, 16, v140
	v_and_b32_e32 v99, 0xffff0000, v140
	v_pk_add_f32 v[86:87], v[86:87], v[94:95]
	v_pk_add_f32 v[84:85], v[84:85], v[92:93]
	v_pk_add_f32 v[94:95], v[80:81], v[98:99]
	v_mul_f32_e32 v80, v85, v85
	v_mul_f32_e32 v81, v87, v87
	v_fmac_f32_e32 v80, v84, v84
	v_fmac_f32_e32 v81, v86, v86
	v_cvt_pk_bf16_f32 v90, v100, v101
	v_lshlrev_b32_e32 v100, 16, v141
	v_and_b32_e32 v101, 0xffff0000, v141
	v_add_f32_e32 v80, v80, v81
	v_mul_f32_e32 v81, v95, v95
	v_pk_add_f32 v[92:93], v[82:83], v[100:101]
	v_fmac_f32_e32 v81, v94, v94
	v_add_f32_e32 v80, v81, v80
	v_mul_f32_e32 v81, v93, v93
	v_fmac_f32_e32 v81, v92, v92
	v_add_f32_e32 v80, v81, v80
	v_add_f32_e32 v83, v102, v80
	v_mov_b32_e32 v100, v83
	s_nop 1
	v_permlane16_swap_b32_e32 v83, v100
	v_lshl_add_u64 v[80:81], s[22:23], 0, v[170:171]
	v_lshl_add_u64 v[98:99], v[158:159], 1, v[80:81]
	v_cvt_pk_bf16_f32 v82, v84, v85
	v_cvt_pk_bf16_f32 v84, v94, v95
	v_add_f32_e32 v80, v83, v100
	v_mov_b32_e32 v81, v80
	s_nop 1
	v_permlane32_swap_b32_e32 v80, v81
	v_add_f32_e32 v80, v80, v81
	v_cvt_pk_bf16_f32 v83, v86, v87
	v_cvt_pk_bf16_f32 v85, v92, v93
	global_store_dwordx4 v[98:99], v[88:91], off
	global_store_dwordx4 v[98:99], v[82:85], off offset:256
	s_and_saveexec_b64 s[40:41], s[36:37]
	s_cbranch_execz .LBB0_322
	v_readlane_b32 s42, v252, 26
	v_lshlrev_b64 v[82:83], 6, v[168:169]
	v_readlane_b32 s43, v252, 27
	s_lshl_b32 s68, s13, 2
	v_lshl_add_u64 v[82:83], s[42:43], 0, v[82:83]
	v_lshl_add_u64 v[82:83], s[30:31], 2, v[82:83]
	v_lshl_add_u64 v[82:83], v[82:83], 0, s[68:69]
	global_store_dword v[82:83], v80, off
.LBB0_322:
	s_or_b64 exec, exec, s[40:41]
	v_lshlrev_b32_e32 v80, 16, v134
	s_waitcnt lgkmcnt(0)
	v_and_b32_e32 v81, 0xffff0000, v134
	v_lshlrev_b32_e32 v82, 16, v135
	v_and_b32_e32 v83, 0xffff0000, v135
	v_lshlrev_b32_e32 v84, 16, v136
	v_and_b32_e32 v85, 0xffff0000, v136
	v_pk_add_f32 v[76:77], v[76:77], v[80:81]
	v_pk_add_f32 v[78:79], v[78:79], v[82:83]
	v_pk_add_f32 v[82:83], v[72:73], v[84:85]
	v_cvt_pk_bf16_f32 v72, v76, v77
	v_mul_f32_e32 v77, v77, v77
	v_fmac_f32_e32 v77, v76, v76
	v_mul_f32_e32 v76, v79, v79
	v_fmac_f32_e32 v76, v78, v78
	v_lshlrev_b32_e32 v86, 16, v137
	v_and_b32_e32 v87, 0xffff0000, v137
	v_add_f32_e32 v76, v77, v76
	v_mul_f32_e32 v77, v83, v83
	v_pk_add_f32 v[80:81], v[74:75], v[86:87]
	v_fmac_f32_e32 v77, v82, v82
	v_add_f32_e32 v76, v77, v76
	v_mul_f32_e32 v77, v81, v81
	v_fmac_f32_e32 v77, v80, v80
	v_cvt_pk_bf16_f32 v73, v78, v79
	v_add_f32_e32 v84, v77, v76
	v_lshlrev_b32_e32 v76, 16, v130
	v_and_b32_e32 v77, 0xffff0000, v130
	v_lshlrev_b32_e32 v78, 16, v131
	v_and_b32_e32 v79, 0xffff0000, v131
	v_cvt_pk_bf16_f32 v75, v80, v81
	v_lshlrev_b32_e32 v80, 16, v132
	v_and_b32_e32 v81, 0xffff0000, v132
	v_pk_add_f32 v[70:71], v[70:71], v[78:79]
	v_pk_add_f32 v[68:69], v[68:69], v[76:77]
	v_pk_add_f32 v[78:79], v[64:65], v[80:81]
	v_mul_f32_e32 v64, v69, v69
	v_mul_f32_e32 v65, v71, v71
	v_fmac_f32_e32 v64, v68, v68
	v_fmac_f32_e32 v65, v70, v70
	v_cvt_pk_bf16_f32 v74, v82, v83
	v_lshlrev_b32_e32 v82, 16, v133
	v_and_b32_e32 v83, 0xffff0000, v133
	v_add_f32_e32 v64, v64, v65
	v_mul_f32_e32 v65, v79, v79
	v_pk_add_f32 v[76:77], v[66:67], v[82:83]
	v_fmac_f32_e32 v65, v78, v78
	v_add_f32_e32 v64, v65, v64
	v_mul_f32_e32 v65, v77, v77
	v_fmac_f32_e32 v65, v76, v76
	v_add_f32_e32 v64, v65, v64
	v_add_f32_e32 v67, v84, v64
	v_mov_b32_e32 v82, v67
	s_nop 1
	v_permlane16_swap_b32_e32 v67, v82
	v_lshl_add_u64 v[64:65], s[22:23], 0, v[166:167]
	v_lshl_add_u64 v[80:81], v[158:159], 1, v[64:65]
	v_cvt_pk_bf16_f32 v66, v68, v69
	v_cvt_pk_bf16_f32 v68, v78, v79
	v_add_f32_e32 v64, v67, v82
	v_mov_b32_e32 v65, v64
	s_nop 1
	v_permlane32_swap_b32_e32 v64, v65
	v_add_f32_e32 v64, v64, v65
	v_cvt_pk_bf16_f32 v67, v70, v71
	v_cvt_pk_bf16_f32 v69, v76, v77
	global_store_dwordx4 v[80:81], v[72:75], off
	global_store_dwordx4 v[80:81], v[66:69], off offset:256
	s_and_saveexec_b64 s[40:41], s[36:37]
	s_cbranch_execz .LBB0_324
	v_readlane_b32 s42, v252, 26
	v_lshlrev_b64 v[66:67], 6, v[164:165]
	v_readlane_b32 s43, v252, 27
	s_lshl_b32 s68, s13, 2
	v_lshl_add_u64 v[66:67], s[42:43], 0, v[66:67]
	v_lshl_add_u64 v[66:67], s[30:31], 2, v[66:67]
	v_lshl_add_u64 v[66:67], v[66:67], 0, s[68:69]
	global_store_dword v[66:67], v64, off
.LBB0_324:
	s_or_b64 exec, exec, s[40:41]
	v_add_u32_e32 v102, 0x80, v160
	v_ashrrev_i32_e32 v103, 31, v102
	v_lshlrev_b64 v[112:113], 11, v[102:103]
	s_waitcnt lgkmcnt(0)
	v_lshl_add_u64 v[64:65], v[162:163], 0, v[112:113]
	global_load_dwordx4 v[104:107], v[64:65], off
	global_load_dwordx4 v[108:111], v[64:65], off offset:256
	v_add_u32_e32 v98, 0x90, v160
	v_ashrrev_i32_e32 v99, 31, v98
	v_add_u32_e32 v92, 0xa0, v160
	v_lshlrev_b64 v[100:101], 11, v[98:99]
	v_ashrrev_i32_e32 v93, 31, v92
	v_add_u32_e32 v88, 0xb0, v160
	v_lshl_add_u64 v[64:65], v[162:163], 0, v[100:101]
	v_lshlrev_b64 v[94:95], 11, v[92:93]
	v_ashrrev_i32_e32 v89, 31, v88
	global_load_dwordx4 v[84:87], v[64:65], off
	global_load_dwordx4 v[80:83], v[64:65], off offset:256
	v_lshl_add_u64 v[64:65], v[162:163], 0, v[94:95]
	v_lshlrev_b64 v[90:91], 11, v[88:89]
	global_load_dwordx4 v[76:79], v[64:65], off
	global_load_dwordx4 v[72:75], v[64:65], off offset:256
	v_lshl_add_u64 v[64:65], v[162:163], 0, v[90:91]
	global_load_dwordx4 v[68:71], v[64:65], off
	s_nop 0
	global_load_dwordx4 v[64:67], v[64:65], off offset:256
	s_waitcnt vmcnt(7)
	v_lshlrev_b32_e32 v114, 16, v104
	v_and_b32_e32 v115, 0xffff0000, v104
	v_lshlrev_b32_e32 v104, 16, v105
	v_and_b32_e32 v105, 0xffff0000, v105
	v_lshlrev_b32_e32 v116, 16, v106
	v_and_b32_e32 v117, 0xffff0000, v106
	v_lshlrev_b32_e32 v106, 16, v107
	v_and_b32_e32 v107, 0xffff0000, v107
	v_pk_add_f32 v[104:105], v[58:59], v[104:105]
	v_pk_add_f32 v[114:115], v[56:57], v[114:115]
	v_pk_add_f32 v[62:63], v[62:63], v[106:107]
	v_pk_add_f32 v[60:61], v[60:61], v[116:117]
	v_lshl_add_u64 v[106:107], s[22:23], 0, v[112:113]
	v_cvt_pk_bf16_f32 v56, v114, v115
	v_cvt_pk_bf16_f32 v57, v104, v105
	v_cvt_pk_bf16_f32 v58, v60, v61
	v_cvt_pk_bf16_f32 v59, v62, v63
	v_lshl_add_u64 v[106:107], v[158:159], 1, v[106:107]
	global_store_dwordx4 v[106:107], v[56:59], off
	s_nop 1
	v_mul_f32_e32 v56, v115, v115
	v_mul_f32_e32 v57, v105, v105
	v_fmac_f32_e32 v56, v114, v114
	v_fmac_f32_e32 v57, v104, v104
	v_add_f32_e32 v56, v56, v57
	v_mul_f32_e32 v57, v61, v61
	v_fmac_f32_e32 v57, v60, v60
	v_add_f32_e32 v56, v57, v56
	v_mul_f32_e32 v57, v63, v63
	v_fmac_f32_e32 v57, v62, v62
	v_add_f32_e32 v104, v57, v56
	s_waitcnt vmcnt(7)
	v_lshlrev_b32_e32 v56, 16, v108
	v_and_b32_e32 v57, 0xffff0000, v108
	v_lshlrev_b32_e32 v58, 16, v109
	v_and_b32_e32 v59, 0xffff0000, v109
	v_lshlrev_b32_e32 v60, 16, v110
	v_and_b32_e32 v61, 0xffff0000, v110
	v_lshlrev_b32_e32 v62, 16, v111
	v_and_b32_e32 v63, 0xffff0000, v111
	v_pk_add_f32 v[54:55], v[54:55], v[58:59]
	v_pk_add_f32 v[52:53], v[52:53], v[56:57]
	v_pk_add_f32 v[56:57], v[50:51], v[62:63]
	v_pk_add_f32 v[58:59], v[48:49], v[60:61]
	v_cvt_pk_bf16_f32 v48, v52, v53
	v_cvt_pk_bf16_f32 v49, v54, v55
	v_cvt_pk_bf16_f32 v50, v58, v59
	v_cvt_pk_bf16_f32 v51, v56, v57
	global_store_dwordx4 v[106:107], v[48:51], off offset:256
	s_nop 1
	v_mul_f32_e32 v48, v53, v53
	v_mul_f32_e32 v49, v55, v55
	v_fmac_f32_e32 v48, v52, v52
	v_fmac_f32_e32 v49, v54, v54
	v_add_f32_e32 v48, v48, v49
	v_mul_f32_e32 v49, v59, v59
	v_fmac_f32_e32 v49, v58, v58
	v_add_f32_e32 v48, v49, v48
	v_mul_f32_e32 v49, v57, v57
	v_fmac_f32_e32 v49, v56, v56
	v_add_f32_e32 v48, v49, v48
	v_add_f32_e32 v48, v104, v48
	v_mov_b32_e32 v49, v48
	s_nop 1
	v_permlane16_swap_b32_e32 v48, v49
	v_add_f32_e32 v48, v48, v49
	v_mov_b32_e32 v49, v48
	s_nop 1
	v_permlane32_swap_b32_e32 v48, v49
	v_add_f32_e32 v48, v48, v49
	s_and_saveexec_b64 s[40:41], s[36:37]
	s_cbranch_execz .LBB0_326
	v_readlane_b32 s42, v252, 26
	v_lshlrev_b64 v[50:51], 6, v[102:103]
	v_readlane_b32 s43, v252, 27
	s_lshl_b32 s68, s13, 2
	v_lshl_add_u64 v[50:51], s[42:43], 0, v[50:51]
	v_lshl_add_u64 v[50:51], s[30:31], 2, v[50:51]
	v_lshl_add_u64 v[50:51], v[50:51], 0, s[68:69]
	global_store_dword v[50:51], v48, off
.LBB0_326:
	s_or_b64 exec, exec, s[40:41]
	s_waitcnt vmcnt(7)
	v_lshlrev_b32_e32 v48, 16, v84
	s_waitcnt lgkmcnt(0)
	v_and_b32_e32 v49, 0xffff0000, v84
	v_lshlrev_b32_e32 v50, 16, v85
	v_and_b32_e32 v51, 0xffff0000, v85
	v_lshlrev_b32_e32 v52, 16, v86
	v_and_b32_e32 v53, 0xffff0000, v86
	v_pk_add_f32 v[44:45], v[44:45], v[48:49]
	v_pk_add_f32 v[46:47], v[46:47], v[50:51]
	v_pk_add_f32 v[50:51], v[40:41], v[52:53]
	v_cvt_pk_bf16_f32 v40, v44, v45
	v_mul_f32_e32 v45, v45, v45
	v_fmac_f32_e32 v45, v44, v44
	v_mul_f32_e32 v44, v47, v47
	v_fmac_f32_e32 v44, v46, v46
	v_lshlrev_b32_e32 v54, 16, v87
	v_and_b32_e32 v55, 0xffff0000, v87
	v_add_f32_e32 v44, v45, v44
	v_mul_f32_e32 v45, v51, v51
	v_pk_add_f32 v[48:49], v[42:43], v[54:55]
	v_fmac_f32_e32 v45, v50, v50
	v_add_f32_e32 v44, v45, v44
	v_mul_f32_e32 v45, v49, v49
	v_fmac_f32_e32 v45, v48, v48
	v_cvt_pk_bf16_f32 v41, v46, v47
	v_add_f32_e32 v52, v45, v44
	s_waitcnt vmcnt(6)
	v_lshlrev_b32_e32 v44, 16, v80
	v_and_b32_e32 v45, 0xffff0000, v80
	v_lshlrev_b32_e32 v46, 16, v81
	v_and_b32_e32 v47, 0xffff0000, v81
	v_cvt_pk_bf16_f32 v43, v48, v49
	v_lshlrev_b32_e32 v48, 16, v82
	v_and_b32_e32 v49, 0xffff0000, v82
	v_pk_add_f32 v[38:39], v[38:39], v[46:47]
	v_pk_add_f32 v[36:37], v[36:37], v[44:45]
	v_pk_add_f32 v[46:47], v[32:33], v[48:49]
	v_mul_f32_e32 v32, v37, v37
	v_mul_f32_e32 v33, v39, v39
	v_fmac_f32_e32 v32, v36, v36
	v_fmac_f32_e32 v33, v38, v38
	v_cvt_pk_bf16_f32 v42, v50, v51
	v_lshlrev_b32_e32 v50, 16, v83
	v_and_b32_e32 v51, 0xffff0000, v83
	v_add_f32_e32 v32, v32, v33
	v_mul_f32_e32 v33, v47, v47
	v_pk_add_f32 v[44:45], v[34:35], v[50:51]
	v_fmac_f32_e32 v33, v46, v46
	v_add_f32_e32 v32, v33, v32
	v_mul_f32_e32 v33, v45, v45
	v_fmac_f32_e32 v33, v44, v44
	v_add_f32_e32 v32, v33, v32
	v_add_f32_e32 v35, v52, v32
	v_mov_b32_e32 v50, v35
	s_nop 1
	v_permlane16_swap_b32_e32 v35, v50
	v_lshl_add_u64 v[32:33], s[22:23], 0, v[100:101]
	v_lshl_add_u64 v[48:49], v[158:159], 1, v[32:33]
	v_cvt_pk_bf16_f32 v34, v36, v37
	v_cvt_pk_bf16_f32 v36, v46, v47
	v_add_f32_e32 v32, v35, v50
	v_mov_b32_e32 v33, v32
	s_nop 1
	v_permlane32_swap_b32_e32 v32, v33
	v_add_f32_e32 v32, v32, v33
	v_cvt_pk_bf16_f32 v35, v38, v39
	v_cvt_pk_bf16_f32 v37, v44, v45
	global_store_dwordx4 v[48:49], v[40:43], off
	global_store_dwordx4 v[48:49], v[34:37], off offset:256
	s_and_saveexec_b64 s[40:41], s[36:37]
	s_cbranch_execz .LBB0_328
	v_readlane_b32 s42, v252, 26
	v_lshlrev_b64 v[34:35], 6, v[98:99]
	v_readlane_b32 s43, v252, 27
	s_lshl_b32 s68, s13, 2
	v_lshl_add_u64 v[34:35], s[42:43], 0, v[34:35]
	v_lshl_add_u64 v[34:35], s[30:31], 2, v[34:35]
	v_lshl_add_u64 v[34:35], v[34:35], 0, s[68:69]
	global_store_dword v[34:35], v32, off
.LBB0_328:
	s_or_b64 exec, exec, s[40:41]
	s_waitcnt vmcnt(7)
	v_lshlrev_b32_e32 v32, 16, v76
	s_waitcnt lgkmcnt(0)
	v_and_b32_e32 v33, 0xffff0000, v76
	v_lshlrev_b32_e32 v34, 16, v77
	v_and_b32_e32 v35, 0xffff0000, v77
	v_lshlrev_b32_e32 v36, 16, v78
	v_and_b32_e32 v37, 0xffff0000, v78
	v_pk_add_f32 v[28:29], v[28:29], v[32:33]
	v_pk_add_f32 v[30:31], v[30:31], v[34:35]
	v_pk_add_f32 v[34:35], v[24:25], v[36:37]
	v_cvt_pk_bf16_f32 v24, v28, v29
	v_mul_f32_e32 v29, v29, v29
	v_fmac_f32_e32 v29, v28, v28
	v_mul_f32_e32 v28, v31, v31
	v_fmac_f32_e32 v28, v30, v30
	v_lshlrev_b32_e32 v38, 16, v79
	v_and_b32_e32 v39, 0xffff0000, v79
	v_add_f32_e32 v28, v29, v28
	v_mul_f32_e32 v29, v35, v35
	v_pk_add_f32 v[32:33], v[26:27], v[38:39]
	v_fmac_f32_e32 v29, v34, v34
	v_add_f32_e32 v28, v29, v28
	v_mul_f32_e32 v29, v33, v33
	v_fmac_f32_e32 v29, v32, v32
	v_cvt_pk_bf16_f32 v25, v30, v31
	v_add_f32_e32 v36, v29, v28
	s_waitcnt vmcnt(6)
	v_lshlrev_b32_e32 v28, 16, v72
	v_and_b32_e32 v29, 0xffff0000, v72
	v_lshlrev_b32_e32 v30, 16, v73
	v_and_b32_e32 v31, 0xffff0000, v73
	v_cvt_pk_bf16_f32 v27, v32, v33
	v_lshlrev_b32_e32 v32, 16, v74
	v_and_b32_e32 v33, 0xffff0000, v74
	v_pk_add_f32 v[22:23], v[22:23], v[30:31]
	v_pk_add_f32 v[20:21], v[20:21], v[28:29]
	v_pk_add_f32 v[30:31], v[16:17], v[32:33]
	v_mul_f32_e32 v16, v21, v21
	v_mul_f32_e32 v17, v23, v23
	v_fmac_f32_e32 v16, v20, v20
	v_fmac_f32_e32 v17, v22, v22
	v_cvt_pk_bf16_f32 v26, v34, v35
	v_lshlrev_b32_e32 v34, 16, v75
	v_and_b32_e32 v35, 0xffff0000, v75
	v_add_f32_e32 v16, v16, v17
	v_mul_f32_e32 v17, v31, v31
	v_pk_add_f32 v[28:29], v[18:19], v[34:35]
	v_fmac_f32_e32 v17, v30, v30
	v_add_f32_e32 v16, v17, v16
	v_mul_f32_e32 v17, v29, v29
	v_fmac_f32_e32 v17, v28, v28
	v_add_f32_e32 v16, v17, v16
	v_add_f32_e32 v19, v36, v16
	v_mov_b32_e32 v34, v19
	s_nop 1
	v_permlane16_swap_b32_e32 v19, v34
	v_lshl_add_u64 v[16:17], s[22:23], 0, v[94:95]
	v_lshl_add_u64 v[32:33], v[158:159], 1, v[16:17]
	v_cvt_pk_bf16_f32 v18, v20, v21
	v_cvt_pk_bf16_f32 v20, v30, v31
	v_add_f32_e32 v16, v19, v34
	v_mov_b32_e32 v17, v16
	s_nop 1
	v_permlane32_swap_b32_e32 v16, v17
	v_add_f32_e32 v16, v16, v17
	v_cvt_pk_bf16_f32 v19, v22, v23
	v_cvt_pk_bf16_f32 v21, v28, v29
	global_store_dwordx4 v[32:33], v[24:27], off
	global_store_dwordx4 v[32:33], v[18:21], off offset:256
	s_and_saveexec_b64 s[40:41], s[36:37]
	s_cbranch_execz .LBB0_330
	v_readlane_b32 s42, v252, 26
	v_lshlrev_b64 v[18:19], 6, v[92:93]
	v_readlane_b32 s43, v252, 27
	s_lshl_b32 s68, s13, 2
	v_lshl_add_u64 v[18:19], s[42:43], 0, v[18:19]
	v_lshl_add_u64 v[18:19], s[30:31], 2, v[18:19]
	v_lshl_add_u64 v[18:19], v[18:19], 0, s[68:69]
	global_store_dword v[18:19], v16, off
.LBB0_330:
	s_or_b64 exec, exec, s[40:41]
	s_waitcnt vmcnt(7)
	v_lshlrev_b32_e32 v16, 16, v68
	s_waitcnt lgkmcnt(0)
	v_and_b32_e32 v17, 0xffff0000, v68
	v_lshlrev_b32_e32 v18, 16, v69
	v_and_b32_e32 v19, 0xffff0000, v69
	v_lshlrev_b32_e32 v20, 16, v70
	v_and_b32_e32 v21, 0xffff0000, v70
	v_pk_add_f32 v[12:13], v[12:13], v[16:17]
	v_pk_add_f32 v[14:15], v[14:15], v[18:19]
	v_pk_add_f32 v[18:19], v[8:9], v[20:21]
	v_cvt_pk_bf16_f32 v8, v12, v13
	v_mul_f32_e32 v13, v13, v13
	v_fmac_f32_e32 v13, v12, v12
	v_mul_f32_e32 v12, v15, v15
	v_fmac_f32_e32 v12, v14, v14
	v_lshlrev_b32_e32 v22, 16, v71
	v_and_b32_e32 v23, 0xffff0000, v71
	v_add_f32_e32 v12, v13, v12
	v_mul_f32_e32 v13, v19, v19
	v_pk_add_f32 v[16:17], v[10:11], v[22:23]
	v_fmac_f32_e32 v13, v18, v18
	v_add_f32_e32 v12, v13, v12
	v_mul_f32_e32 v13, v17, v17
	v_fmac_f32_e32 v13, v16, v16
	v_cvt_pk_bf16_f32 v9, v14, v15
	v_add_f32_e32 v20, v13, v12
	s_waitcnt vmcnt(6)
	v_lshlrev_b32_e32 v12, 16, v64
	v_and_b32_e32 v13, 0xffff0000, v64
	v_lshlrev_b32_e32 v14, 16, v65
	v_and_b32_e32 v15, 0xffff0000, v65
	v_cvt_pk_bf16_f32 v11, v16, v17
	v_lshlrev_b32_e32 v16, 16, v66
	v_and_b32_e32 v17, 0xffff0000, v66
	v_pk_add_f32 v[6:7], v[6:7], v[14:15]
	v_pk_add_f32 v[4:5], v[4:5], v[12:13]
	v_pk_add_f32 v[14:15], v[0:1], v[16:17]
	v_mul_f32_e32 v0, v5, v5
	v_mul_f32_e32 v1, v7, v7
	v_fmac_f32_e32 v0, v4, v4
	v_fmac_f32_e32 v1, v6, v6
	v_cvt_pk_bf16_f32 v10, v18, v19
	v_lshlrev_b32_e32 v18, 16, v67
	v_and_b32_e32 v19, 0xffff0000, v67
	v_add_f32_e32 v0, v0, v1
	v_mul_f32_e32 v1, v15, v15
	v_pk_add_f32 v[12:13], v[2:3], v[18:19]
	v_fmac_f32_e32 v1, v14, v14
	v_add_f32_e32 v0, v1, v0
	v_mul_f32_e32 v1, v13, v13
	v_fmac_f32_e32 v1, v12, v12
	v_add_f32_e32 v0, v1, v0
	v_add_f32_e32 v3, v20, v0
	v_mov_b32_e32 v18, v3
	s_nop 1
	v_permlane16_swap_b32_e32 v3, v18
	v_lshl_add_u64 v[0:1], s[22:23], 0, v[90:91]
	v_lshl_add_u64 v[16:17], v[158:159], 1, v[0:1]
	v_cvt_pk_bf16_f32 v2, v4, v5
	v_cvt_pk_bf16_f32 v4, v14, v15
	v_add_f32_e32 v0, v3, v18
	v_mov_b32_e32 v1, v0
	s_nop 1
	v_permlane32_swap_b32_e32 v0, v1
	v_add_f32_e32 v0, v0, v1
	v_cvt_pk_bf16_f32 v3, v6, v7
	v_cvt_pk_bf16_f32 v5, v12, v13
	global_store_dwordx4 v[16:17], v[8:11], off
	global_store_dwordx4 v[16:17], v[2:5], off offset:256
	s_and_saveexec_b64 s[40:41], s[36:37]
	s_cbranch_execz .LBB0_332
	v_readlane_b32 s42, v252, 26
	v_lshlrev_b64 v[2:3], 6, v[88:89]
	v_readlane_b32 s43, v252, 27
	s_lshl_b32 s68, s13, 2
	v_lshl_add_u64 v[2:3], s[42:43], 0, v[2:3]
	v_lshl_add_u64 v[2:3], s[30:31], 2, v[2:3]
	v_lshl_add_u64 v[2:3], v[2:3], 0, s[68:69]
	global_store_dword v[2:3], v0, off

.Lglobal_bar:
	s_cmp_eq_u32 s100, 0
	s_cbranch_scc1 .Lwb
	s_cmp_eq_u32 s73, 6
	s_cbranch_scc1 .Lno_wb
	s_cmp_eq_u32 s73, 8
	s_cbranch_scc1 .Lno_wb
	s_cmp_eq_u32 s73, 14
	s_cbranch_scc1 .Lno_wb

.Lno_wb:
	s_waitcnt lgkmcnt(0)
	s_waitcnt vmcnt(0)
	v_mbcnt_lo_u32_b32 v1, s30, 0
	v_mbcnt_hi_u32_b32 v1, s31, v1
	v_cmp_eq_u32_e32 vcc, 0, v1
	s_and_saveexec_b64 s[36:37], vcc
	s_cbranch_execz .LBB0_614
	s_bcnt1_i32_b64 s2, s[30:31]
	v_readlane_b32 s4, v253, 41
	v_mov_b32_e32 v2, s2
	v_readlane_b32 s5, v253, 42
	s_nop 4
	global_atomic_add v2, v97, v2, s[4:5] sc0
